# helper derive/M stages: loop-invariant per-lane address and mask computations hoisted out of the chunk loop (computed once per chain), masks applied by multiplication
# speedup vs baseline: 1.0079x; 1.0079x over previous
.Lmy_f_l669:
	s_or_b64 exec, exec, s[96:97]
	v_lshlrev_b64 v[158:159], 13, v[158:159]
	v_lshl_add_u64 v[158:159], v[52:53], 0, v[158:159]
	v_mov_b32_e32 v178, v158
	v_mov_b32_e32 v179, v159
	v_add_co_u32_e32 v160, vcc, 0x1000, v158
	s_nop 1
	v_addc_co_u32_e32 v161, vcc, 0, v159, vcc
	global_load_dwordx2 v[158:159], v[158:159], off
	s_nop 0
	global_load_dwordx2 v[160:161], v[160:161], off
	v_subrev_u32_e32 v70, s100, v70
	v_add_u32_e32 v71, s100, v71
	s_mov_b32 s96, 0xffffe000
	s_mov_b32 s97, -1
	v_lshl_add_u64 v[164:165], v[166:167], 0, s[96:97]
	v_lshl_add_u64 v[172:173], v[174:175], 0, s[96:97]
	s_mov_b32 s96, 0x2000
	s_mov_b32 s97, 0
	v_lshl_add_u64 v[168:169], v[166:167], 0, s[96:97]
	v_lshl_add_u64 v[176:177], v[174:175], 0, s[96:97]
	s_mov_b32 s96, 0x800
	v_lshl_add_u64 v[170:171], v[170:171], 0, s[96:97]
	v_lshl_add_u64 v[178:179], v[178:179], 0, s[96:97]
	s_bfe_u32 s96, s62, 0x20006
	s_lshl_b32 s96, s96, 11
	v_lshl_add_u32 v198, v224, 2, s96
	v_and_b32_e32 v217, 3, v224
	v_bfe_u32 v218, v224, 2, 2
	v_lshrrev_b32_e32 v219, 4, v224
	v_lshlrev_b32_e32 v217, 2, v217
	v_lshl_add_u32 v217, v218, 8, v217
	v_lshl_add_u32 v217, v219, 10, v217
	v_xor_b32_e32 v200, 0, v218
	v_lshl_add_u32 v200, v200, 4, v217
	v_xor_b32_e32 v201, 1, v218
	v_lshl_add_u32 v201, v201, 4, v217
	v_xor_b32_e32 v202, 2, v218
	v_lshl_add_u32 v202, v202, 4, v217
	v_xor_b32_e32 v203, 3, v218
	v_lshl_add_u32 v203, v203, 4, v217
	v_and_b32_e32 v204, 15, v224
	v_lshlrev_b32_e32 v204, 4, v204
	v_lshl_add_u32 v204, v219, 10, v204
	v_lshlrev_b32_e32 v205, 2, v224
	v_and_b32_e32 v206, 3, v233
	v_lshrrev_b32_e32 v220, 2, v233
	v_lshlrev_b32_e32 v206, 2, v206
	v_lshl_add_u32 v206, v220, 8, v206
	v_lshl_add_u32 v206, v234, 6, v206
	v_xor_b32_e32 v207, v224, v234
	v_lshlrev_b32_e32 v207, 4, v207
	v_lshlrev_b32_e32 v216, 7, v234
	v_lshl_add_u32 v216, v233, 2, v216
	v_add_u32_e32 v217, -1, v233
	v_mov_b32_e32 v218, -1
	v_cndmask_b32_e64 v217, v218, v217, s[98:99]
	v_cmp_lt_u32_e32 vcc, 7, v233
	v_add_u32_e32 v218, -8, v233
	v_and_b32_e32 v219, 1, v234
	s_nop 1
	v_cndmask_b32_e32 v217, v217, v218, vcc
	v_lshlrev_b32_e32 v219, 2, v219
	v_sub_u32_e32 v217, v217, v219
	v_lshlrev_b32_e32 v219, 2, v234
	v_sub_u32_e32 v218, v233, v219
	v_add_u32_e32 v218, -1, v218
	v_cmp_le_i32_e32 vcc, 0, v217
	s_nop 1
	v_cndmask_b32_e64 v208, 0, 1.0, vcc
	v_cmp_le_i32_e32 vcc, 1, v217
	s_nop 1
	v_cndmask_b32_e64 v209, 0, 1.0, vcc
	v_cmp_le_i32_e32 vcc, 2, v217
	s_nop 1
	v_cndmask_b32_e64 v210, 0, 1.0, vcc
	v_cmp_le_i32_e32 vcc, 3, v217
	s_nop 1
	v_cndmask_b32_e64 v211, 0, 1.0, vcc
	v_cmp_le_i32_e32 vcc, 0, v218
	s_nop 1
	v_cndmask_b32_e64 v212, 0, 1.0, vcc
	v_cmp_le_i32_e32 vcc, 1, v218
	s_nop 1
	v_cndmask_b32_e64 v213, 0, 1.0, vcc
	v_cmp_le_i32_e32 vcc, 2, v218
	s_nop 1
	v_cndmask_b32_e64 v214, 0, 1.0, vcc
	v_cmp_le_i32_e32 vcc, 3, v218
	s_nop 1
	v_cndmask_b32_e64 v215, 0, 1.0, vcc

.Lmy_f_nol34:
	s_waitcnt lgkmcnt(0)
	s_bfe_u32 s96, s62, 0x20006
	s_and_b32 s97, s96, 1
	s_mul_i32 s97, s97, 0x2700
	s_mov_b32 s101, 0x1c000
	s_mov_b32 s100, 0x6100
	s_bitcmp0_b32 s65, 0
	s_cselect_b32 s101, 0xe000, s101
	s_cselect_b32 s100, 0x4e00, s100
	s_cmp_gt_u32 s96, 1
	s_cselect_b32 s100, s100, 0
	s_add_i32 s97, s97, s101
	s_add_i32 s97, s97, s100
	ds_read_b32 v80, v198
	ds_read_b32 v81, v198 offset:256
	ds_read_b32 v82, v198 offset:512
	ds_read_b32 v83, v198 offset:768
	ds_read_b32 v84, v198 offset:1024
	ds_read_b32 v85, v198 offset:1280
	ds_read_b32 v86, v198 offset:1536
	ds_read_b32 v87, v198 offset:1792
	ds_read_b32 v88, v198 offset:8192
	ds_read_b32 v89, v198 offset:8448
	ds_read_b32 v90, v198 offset:8704
	ds_read_b32 v91, v198 offset:8960
	ds_read_b32 v92, v198 offset:9216
	ds_read_b32 v93, v198 offset:9472
	ds_read_b32 v94, v198 offset:9728
	ds_read_b32 v95, v198 offset:9984
	ds_read_b32 v96, v198 offset:32768
	ds_read_b32 v97, v198 offset:33024
	ds_read_b32 v98, v198 offset:33280
	ds_read_b32 v99, v198 offset:33536
	ds_read_b32 v100, v198 offset:33792
	ds_read_b32 v101, v198 offset:34048
	ds_read_b32 v102, v198 offset:34304
	ds_read_b32 v103, v198 offset:34560
	s_add_i32 s100, s97, 0x0
	v_add_u32_e32 v76, s100, v200
	v_add_u32_e32 v77, s100, v201
	v_add_u32_e32 v78, s100, v202
	v_add_u32_e32 v79, s100, v203
	s_waitcnt lgkmcnt(15)
	v_mov_b32_e32 v104, v80
	v_mul_f32_e32 v105, v104, v81
	v_mul_f32_e32 v106, v105, v82
	v_mul_f32_e32 v107, v106, v83
	v_mul_f32_e32 v108, v107, v84
	v_mul_f32_e32 v109, v108, v85
	v_mul_f32_e32 v110, v109, v86
	v_mul_f32_e32 v111, v110, v87
	v_mov_b32_e32 v112, v88
	s_waitcnt lgkmcnt(14)
	v_mul_f32_e32 v113, v104, v89
	s_waitcnt lgkmcnt(13)
	v_mul_f32_e32 v114, v105, v90
	s_waitcnt lgkmcnt(12)
	v_mul_f32_e32 v115, v106, v91
	s_waitcnt lgkmcnt(11)
	v_mul_f32_e32 v116, v107, v92
	s_waitcnt lgkmcnt(10)
	v_mul_f32_e32 v117, v108, v93
	s_waitcnt lgkmcnt(9)
	v_mul_f32_e32 v118, v109, v94
	s_waitcnt lgkmcnt(8)
	v_mul_f32_e32 v119, v110, v95
	s_waitcnt lgkmcnt(7)
	v_mul_f32_e32 v120, v104, v96
	s_waitcnt lgkmcnt(6)
	v_mul_f32_e32 v121, v105, v97
	s_waitcnt lgkmcnt(5)
	v_mul_f32_e32 v122, v106, v98
	s_waitcnt lgkmcnt(4)
	v_mul_f32_e32 v123, v107, v99
	s_waitcnt lgkmcnt(3)
	v_mul_f32_e32 v124, v108, v100
	s_waitcnt lgkmcnt(2)
	v_mul_f32_e32 v125, v109, v101
	s_waitcnt lgkmcnt(1)
	v_mul_f32_e32 v126, v110, v102
	s_waitcnt lgkmcnt(0)
	v_mul_f32_e32 v127, v111, v103
	ds_write_b32 v76, v112
	ds_write_b32 v77, v113
	ds_write_b32 v78, v114
	ds_write_b32 v79, v115
	ds_write_b32 v76, v116 offset:64
	ds_write_b32 v77, v117 offset:64
	ds_write_b32 v78, v118 offset:64
	ds_write_b32 v79, v119 offset:64
	ds_write_b32 v76, v120 offset:128
	ds_write_b32 v77, v121 offset:128
	ds_write_b32 v78, v122 offset:128
	ds_write_b32 v79, v123 offset:128
	ds_write_b32 v76, v124 offset:192
	ds_write_b32 v77, v125 offset:192
	ds_write_b32 v78, v126 offset:192
	ds_write_b32 v79, v127 offset:192
	s_waitcnt lgkmcnt(0)
	ds_read_b32 v88, v198 offset:16384
	ds_read_b32 v89, v198 offset:16640
	ds_read_b32 v90, v198 offset:16896
	ds_read_b32 v91, v198 offset:17152
	ds_read_b32 v92, v198 offset:17408
	ds_read_b32 v93, v198 offset:17664
	ds_read_b32 v94, v198 offset:17920
	ds_read_b32 v95, v198 offset:18176
	ds_read_b32 v96, v198 offset:24576
	ds_read_b32 v97, v198 offset:24832
	ds_read_b32 v98, v198 offset:25088
	ds_read_b32 v99, v198 offset:25344
	ds_read_b32 v100, v198 offset:25600
	ds_read_b32 v101, v198 offset:25856
	ds_read_b32 v102, v198 offset:26112
	ds_read_b32 v103, v198 offset:26368
	s_add_i32 s101, s97, 0x1000
	v_add_u32_e32 v74, s101, v204
	s_add_i32 s101, s97, 0x2000
	v_add_u32_e32 v75, s101, v205
	v_rcp_f32_e32 v112, v104
	v_rcp_f32_e32 v113, v105
	v_rcp_f32_e32 v114, v106
	v_rcp_f32_e32 v115, v107
	v_rcp_f32_e32 v116, v108
	v_rcp_f32_e32 v117, v109
	v_rcp_f32_e32 v118, v110
	v_rcp_f32_e32 v119, v111
	s_waitcnt lgkmcnt(7)
	v_mul_f32_e32 v120, v112, v96
	s_waitcnt lgkmcnt(6)
	v_mul_f32_e32 v121, v113, v97
	s_waitcnt lgkmcnt(5)
	v_mul_f32_e32 v122, v114, v98
	s_waitcnt lgkmcnt(4)
	v_mul_f32_e32 v123, v115, v99
	s_waitcnt lgkmcnt(3)
	v_mul_f32_e32 v124, v116, v100
	s_waitcnt lgkmcnt(2)
	v_mul_f32_e32 v125, v117, v101
	s_waitcnt lgkmcnt(1)
	v_mul_f32_e32 v126, v118, v102
	s_waitcnt lgkmcnt(0)
	v_mul_f32_e32 v127, v119, v103
	v_mul_f32_e32 v112, v112, v88
	v_mul_f32_e32 v113, v113, v89
	v_mul_f32_e32 v114, v114, v90
	v_mul_f32_e32 v115, v115, v91
	v_mul_f32_e32 v116, v116, v92
	v_mul_f32_e32 v117, v117, v93
	v_mul_f32_e32 v118, v118, v94
	v_mul_f32_e32 v119, v119, v95
	ds_write_b128 v74, v[112:115]
	ds_write_b128 v74, v[116:119] offset:256
	ds_write_b128 v74, v[120:123] offset:512
	ds_write_b128 v74, v[124:127] offset:768
	ds_write_b32 v75, v111
	s_waitcnt lgkmcnt(0)
	s_bfe_u32 s96, s62, 0x20006
	s_and_b32 s97, s96, 1
	s_mul_i32 s97, s97, 0x2700
	s_mov_b32 s101, 0x1c000
	s_mov_b32 s100, 0x6100
	s_bitcmp0_b32 s65, 0
	s_cselect_b32 s101, 0xe000, s101
	s_cselect_b32 s100, 0x4e00, s100
	s_cmp_gt_u32 s96, 1
	s_cselect_b32 s100, s100, 0
	s_add_i32 s97, s97, s101
	s_add_i32 s97, s97, s100
	s_mov_b32 s96, s97
	s_add_i32 s101, s96, 0x1000
	v_add_u32_e32 v78, s101, v206
	v_add_u32_e32 v79, s96, v207
	ds_read_b128 v[96:99], v79
	ds_read_b128 v[100:103], v79 offset:1024
	ds_read_b128 v[104:107], v79 offset:2048
	ds_read_b128 v[108:111], v79 offset:3072
	ds_read_b32 v80, v78
	ds_read_b32 v81, v78 offset:16
	ds_read_b32 v82, v78 offset:32
	ds_read_b32 v83, v78 offset:48
	ds_read_b32 v84, v78 offset:1024
	ds_read_b32 v85, v78 offset:1040
	ds_read_b32 v86, v78 offset:1056
	ds_read_b32 v87, v78 offset:1072
	ds_read_b32 v88, v78 offset:2048
	ds_read_b32 v89, v78 offset:2064
	ds_read_b32 v90, v78 offset:2080
	ds_read_b32 v91, v78 offset:2096
	ds_read_b32 v92, v78 offset:3072
	ds_read_b32 v93, v78 offset:3088
	ds_read_b32 v94, v78 offset:3104
	ds_read_b32 v95, v78 offset:3120
	v_add_u32_e32 v74, s96, v205
	ds_write_b32 v74, v235 offset:9728
	s_waitcnt lgkmcnt(15)
	v_mfma_f32_16x16x4_f32 v[244:247], v80, v96, 0
	v_mfma_f32_16x16x4_f32 v[240:243], v81, v97, 0
	s_waitcnt lgkmcnt(14)
	v_mfma_f32_16x16x4_f32 v[244:247], v82, v98, v[244:247]
	s_waitcnt lgkmcnt(13)
	v_mfma_f32_16x16x4_f32 v[240:243], v83, v99, v[240:243]
	s_waitcnt lgkmcnt(12)
	v_mfma_f32_16x16x4_f32 v[244:247], v84, v100, v[244:247]
	s_waitcnt lgkmcnt(11)
	v_mfma_f32_16x16x4_f32 v[240:243], v85, v101, v[240:243]
	s_waitcnt lgkmcnt(10)
	v_mfma_f32_16x16x4_f32 v[244:247], v86, v102, v[244:247]
	s_waitcnt lgkmcnt(9)
	v_mfma_f32_16x16x4_f32 v[240:243], v87, v103, v[240:243]
	s_waitcnt lgkmcnt(8)
	v_mfma_f32_16x16x4_f32 v[244:247], v88, v104, v[244:247]
	s_waitcnt lgkmcnt(7)
	v_mfma_f32_16x16x4_f32 v[240:243], v89, v105, v[240:243]
	s_waitcnt lgkmcnt(6)
	v_mfma_f32_16x16x4_f32 v[244:247], v90, v106, v[244:247]
	s_waitcnt lgkmcnt(5)
	v_mfma_f32_16x16x4_f32 v[240:243], v91, v107, v[240:243]
	s_waitcnt lgkmcnt(4)
	v_mfma_f32_16x16x4_f32 v[244:247], v92, v108, v[244:247]
	s_waitcnt lgkmcnt(3)
	v_mfma_f32_16x16x4_f32 v[240:243], v93, v109, v[240:243]
	s_waitcnt lgkmcnt(2)
	v_mfma_f32_16x16x4_f32 v[244:247], v94, v110, v[244:247]
	s_waitcnt lgkmcnt(1)
	v_mfma_f32_16x16x4_f32 v[240:243], v95, v111, v[240:243]
	s_nop 9
	v_add_f32_e32 v244, v244, v240
	v_add_f32_e32 v245, v245, v241
	v_add_f32_e32 v246, v246, v242
	v_add_f32_e32 v247, v247, v243
	v_mul_f32_e32 v128, v244, v208
	v_mul_f32_e32 v129, v245, v209
	v_mul_f32_e32 v130, v246, v210
	v_mul_f32_e32 v131, v247, v211
	ds_write_b128 v79, v[128:131] offset:8448
	v_add_u32_e32 v75, s96, v216
	v_mul_f32_e32 v132, v244, v212
	v_mul_f32_e32 v133, v245, v213
	v_mul_f32_e32 v134, v246, v214
	v_mul_f32_e32 v135, v247, v215
	s_mov_b64 exec, 0x00ff00ff
	ds_write_b32 v75, v132 offset:9472
	ds_write_b32 v75, v133 offset:9504
	ds_write_b32 v75, v134 offset:9536
	ds_write_b32 v75, v135 offset:9568
	s_mov_b64 exec, -1
	s_setprio 0
	s_branch .LBB0_655
	s_nop 0
